# v15 + attn unit prologue: first mask-row load issued before the K/V tile waits and barrier (vmcnt 1/0 -> 2/1)
# baseline (speedup 1.0000x reference)
; template <int PV> __device__ __forceinline__ void dsa_attn(const Args& a, unsigned char* lds, int tid) {
;     ...
;         u32x4 kr0 = *(const u32x4*)kg, vr0 = *(const u32x4*)vg, kr1 = kr0, vr1 = vr0;
;         if (ntile > 1) { kr1 = *(const u32x4*)(kg + (size_t)64 * 256); vr1 = *(const u32x4*)(vg + 64); }
;         *(u32x4*)(ksm + srow * 72 + sc16 * 8) = kr0; *(u32x4*)(vsm + srow * 72 + sc16 * 8) = vr0;
;         *(u32x4*)(ksm + 64 * 72 + srow * 72 + sc16 * 8) = kr1; *(u32x4*)(vsm + 64 * 72 + srow * 72 + sc16 * 8) = vr1;
;         __syncthreads();
;         f32x16 o0, o1;
; #pragma unroll
;         for (int e = 0; e < 16; ++e) { o0[e] = 0.f; o1[e] = 0.f; }
;         float lsum = 0.f;
;         u64 mwa = mrow[0], mwb = (ntile > 1) ? mrow[1] : 0ull;
.LBB0_1000:
	v_readlane_b32 s14, v249, 39
	v_lshlrev_b64 v[196:197], 9, v[18:19]
	v_readlane_b32 s15, v249, 40
	ds_write_b128 v214, v[152:155]
	ds_write_b128 v214, v[156:159] offset:36864
	s_nop 1
	v_lshl_add_u64 v[18:19], s[14:15], 0, v[196:197]
	global_load_dwordx2 v[64:65], v[18:19], off
	s_waitcnt vmcnt(2)
	ds_write_b128 v214, v[160:163] offset:9216
	s_waitcnt vmcnt(1)
	ds_write_b128 v214, v[164:167] offset:46080
	s_waitcnt lgkmcnt(0)
	s_barrier
	s_and_b64 vcc, exec, s[2:3]
	s_cbranch_vccz .LBB0_1002
	global_load_dwordx2 v[96:97], v[18:19], off offset:8
	s_branch .LBB0_1003
